# X2 sample q tile: LDS row pitch 576 B to spread the fragment reads over the banks
# baseline (speedup 1.0000x reference)
; #define LAS __attribute__((address_space(3)))
; __device__ __forceinline__ float bf_lo(unsigned w) { return __uint_as_float(w << 16); }
; __device__ __forceinline__ float bf_hi(unsigned w) { return __uint_as_float(w & 0xffff0000u); }
; __device__ __forceinline__ void xattn_sample_block(LAS unsigned char* lds, const bf16_t* xq, const bf16_t* xq1, const float* mk, const float* mv, bf16_t* xo, int it, int tid) {
;     const int h = it & 3, b = it >> 2, wave = tid >> 6, lane = tid & 63;
;     LAS float* qs = (LAS float*)lds;
;     LAS float* pT = qs + 1024;
;     LAS float* ml = pT + 2048;
;     LAS float* po = ml + 64;
;     const size_t tok0 = (size_t)T_P + b * 8;
;     if (wave < 4) {
; #pragma unroll
;         for (int t2 = 0; t2 < 2; ++t2) {
;             const int t = wave * 2 + t2;
;             const unsigned qw = *(const unsigned*)(xq + (tok0 + t) * 512 + h * 128 + 2 * lane), qw1 = *(const unsigned*)(xq1 + (tok0 + t) * 512 + h * 128 + 2 * lane);
;             *(LAS f32x2*)(qs + t * 128 + 2 * lane) = (f32x2){(bf_lo(qw) + bf_lo(qw1)) * 0.08838834764831845f, (bf_hi(qw) + bf_hi(qw1)) * 0.08838834764831845f};
;         }
;     }
;     __syncthreads();
;     if (wave < 4) {
;         const int key = lane + 64 * wave;
;         float s[8];
; #pragma unroll
;         for (int t = 0; t < 8; ++t) s[t] = 0.f;
;         const f32x4* kp = (const f32x4*)(mk + (((size_t)b * 256 + key) * 4 + h) * 128);
; #pragma unroll 8
;         for (int d4 = 0; d4 < 32; ++d4) {
;             const f32x4 k4 = kp[d4];
; #pragma unroll
;             for (int t = 0; t < 8; ++t) { const f32x4 q4 = *(const LAS f32x4*)(qs + t * 128 + 4 * d4); s[t] += (k4[0] * q4[0] + k4[1] * q4[1]) + (k4[2] * q4[2] + k4[3] * q4[3]); }
;         }
.LBB0_1371:
	v_readlane_b32 s6, v254, 0
	s_cmp_ge_i32 s52, s6
	s_cselect_b64 s[8:9], -1, 0
	s_and_b64 s[4:5], s[4:5], s[8:9]
	s_andn2_b64 vcc, exec, s[4:5]
	v_readlane_b32 s7, v254, 1
	s_cbranch_vccnz .LBB0_1405
	v_mov_b32_e32 v18, v139
	s_mov_b32 s26, s90
	s_mov_b32 s4, 5
	s_ashr_i32 s5, s4, 31
	s_lshl_b64 s[4:5], s[4:5], 3
	s_add_u32 s4, s96, s4
	s_addc_u32 s5, s97, s5
	s_load_dwordx2 s[22:23], s[4:5], 0x0
	s_mov_b32 s4, 6
	s_waitcnt lgkmcnt(0)
	s_ashr_i32 s5, s4, 31
	s_lshl_b64 s[4:5], s[4:5], 3
	s_add_u32 s4, s96, s4
	s_addc_u32 s5, s97, s5
	s_load_dwordx2 s[20:21], s[4:5], 0x0
	v_readlane_b32 s4, v254, 40
	v_readlane_b32 s5, v254, 41
	v_readlane_b32 s6, v254, 42
	v_readlane_b32 s7, v254, 43
	s_mov_b64 s[4:5], s[6:7]
	s_waitcnt lgkmcnt(0)
	s_add_u32 s10, s4, 0x29228000
	s_addc_u32 s11, s5, 0
	s_mov_b64 s[4:5], s[6:7]
	s_add_u32 s12, s4, 0x13e08000
	s_addc_u32 s13, s5, 0
	s_mov_b64 s[4:5], s[6:7]
	s_add_u32 s14, s4, 0x29a68000
	s_addc_u32 s15, s5, 0
	v_and_b32_e32 v44, 63, v18
	v_readfirstlane_b32 s27, v18
	s_mov_b64 s[18:19], s[6:7]
	s_mov_b64 s[16:17], s[6:7]
	s_mov_b64 s[4:5], s[6:7]
	s_cmp_ge_i32 s26, s82
	s_cbranch_scc0 .LBB0_1402
	s_sub_i32 s28, s26, s82
	s_cmpk_gt_i32 s28, 0x7f
	s_cbranch_scc1 .LBB0_1402
	v_readlane_b32 s24, v254, 36
	v_readlane_b32 s25, v254, 37
	v_and_b32_e32 v50, 15, v215
	v_lshrrev_b32_e32 v51, 4, v215
	s_lshr_b32 s29, s27, 6
	s_add_u32 s22, s22, s24
	s_addc_u32 s23, s23, s25
	s_add_u32 s20, s20, s24
	s_addc_u32 s21, s21, s25
	s_lshl_b32 s30, s29, 16
	v_lshlrev_b32_e32 v52, 11, v50
	v_lshl_add_u32 v52, v51, 4, v52
	v_add_u32_e32 v52, s30, v52
	v_lshlrev_b32_e32 v53, 13, v51
	v_lshl_add_u32 v53, v50, 4, v53
	v_add_u32_e32 v53, s30, v53
	v_and_b32_e32 v54, 7, v50
	v_mul_u32_u24_e32 v54, 0x240, v54
	v_lshl_add_u32 v54, v51, 4, v54
	v_lshlrev_b32_e32 v55, 2, v139
	v_xor_b32_e32 v56, 16, v215
	v_lshlrev_b32_e32 v56, 2, v56
	v_xor_b32_e32 v57, 32, v215
	v_lshlrev_b32_e32 v57, 2, v57
.Lxs_item:
	s_and_b32 s31, s28, 3
	s_lshr_b32 s4, s28, 2
	s_lshl_b32 s5, s4, 19
	s_lshl_b32 s6, s31, 9
	s_add_i32 s5, s5, s6
	s_add_u32 s16, s22, s5
	s_addc_u32 s17, s23, 0
	s_add_u32 s18, s20, s5
	s_addc_u32 s19, s21, 0
	global_load_dwordx4 v[64:67], v52, s[16:17] offset:0
	global_load_dwordx4 v[68:71], v52, s[16:17] offset:64
	global_load_dwordx4 v[72:75], v52, s[16:17] offset:128
	global_load_dwordx4 v[76:79], v52, s[16:17] offset:192
	global_load_dwordx4 v[80:83], v52, s[16:17] offset:256
	global_load_dwordx4 v[84:87], v52, s[16:17] offset:320
	global_load_dwordx4 v[88:91], v52, s[16:17] offset:384
	global_load_dwordx4 v[92:95], v52, s[16:17] offset:448
	s_add_u32 s16, s16, 0x8000
	s_addc_u32 s17, s17, 0
	global_load_dwordx4 v[96:99], v52, s[16:17] offset:0
	global_load_dwordx4 v[100:103], v52, s[16:17] offset:64
	global_load_dwordx4 v[104:107], v52, s[16:17] offset:128
	global_load_dwordx4 v[108:111], v52, s[16:17] offset:192
	global_load_dwordx4 v[112:115], v52, s[16:17] offset:256
	global_load_dwordx4 v[116:119], v52, s[16:17] offset:320
	global_load_dwordx4 v[120:123], v52, s[16:17] offset:384
	global_load_dwordx4 v[124:127], v52, s[16:17] offset:448
	s_lshl_b32 s5, s4, 3
	s_addk_i32 s5, 0x2000
	s_lshl_b32 s5, s5, 10
	s_lshl_b32 s6, s31, 8
	s_add_i32 s5, s5, s6
	s_add_u32 s24, s10, s5
	s_addc_u32 s25, s11, 0
	v_lshrrev_b32_e32 v58, 6, v139
	v_and_b32_e32 v59, 63, v139
	v_lshlrev_b32_e32 v60, 10, v58
	v_lshl_add_u32 v60, v59, 2, v60
	global_load_dword v61, v60, s[24:25]
	s_add_u32 s24, s12, s5
	s_addc_u32 s25, s13, 0
	global_load_dword v62, v60, s[24:25]
	global_load_dwordx4 v[146:149], v53, s[18:19] offset:0
	global_load_dwordx4 v[150:153], v53, s[18:19] offset:256
	s_add_u32 s18, s18, 0x800
	s_addc_u32 s19, s19, 0
	global_load_dwordx4 v[154:157], v53, s[18:19] offset:0
	global_load_dwordx4 v[158:161], v53, s[18:19] offset:256
	s_add_u32 s18, s18, 0x800
	s_addc_u32 s19, s19, 0
	global_load_dwordx4 v[162:165], v53, s[18:19] offset:0
	global_load_dwordx4 v[166:169], v53, s[18:19] offset:256
	s_add_u32 s18, s18, 0x800
	s_addc_u32 s19, s19, 0
	global_load_dwordx4 v[170:173], v53, s[18:19] offset:0
	global_load_dwordx4 v[174:177], v53, s[18:19] offset:256
	s_add_u32 s18, s18, 0x6800
	s_addc_u32 s19, s19, 0
	global_load_dwordx4 v[178:181], v53, s[18:19] offset:0
	global_load_dwordx4 v[182:185], v53, s[18:19] offset:256
	s_add_u32 s18, s18, 0x800
	s_addc_u32 s19, s19, 0
	global_load_dwordx4 v[186:189], v53, s[18:19] offset:0
	global_load_dwordx4 v[190:193], v53, s[18:19] offset:256
	s_add_u32 s18, s18, 0x800
	s_addc_u32 s19, s19, 0
	global_load_dwordx4 v[194:197], v53, s[18:19] offset:0
	global_load_dwordx4 v[198:201], v53, s[18:19] offset:256
	s_add_u32 s18, s18, 0x800
	s_addc_u32 s19, s19, 0
	global_load_dwordx4 v[202:205], v53, s[18:19] offset:0
	global_load_dwordx4 v[206:209], v53, s[18:19] offset:256
	s_waitcnt vmcnt(16)
	v_lshlrev_b32_e32 v46, 16, v61
	v_and_b32_e32 v47, 0xffff0000, v61
	v_lshlrev_b32_e32 v48, 16, v62
	v_and_b32_e32 v49, 0xffff0000, v62
	v_pk_add_f32 v[46:47], v[46:47], v[48:49]
	v_pk_mul_f32 v[46:47], v[46:47], s[86:87] op_sel_hi:[1,0]
	v_mul_u32_u24_e32 v60, 0x240, v58
	v_lshl_add_u32 v60, v59, 3, v60
	ds_write_b64 v60, v[46:47]
	s_waitcnt lgkmcnt(0)
	s_barrier
; #define LAS __attribute__((address_space(3)))
; __device__ __forceinline__ void xattn_sample_block(LAS unsigned char* lds, const bf16_t* xq, const bf16_t* xq1, const float* mk, const float* mv, bf16_t* xo, int it, int tid) {
;     ...
;         const f32x4* kp = (const f32x4*)(mk + (((size_t)b * 256 + key) * 4 + h) * 128);
; #pragma unroll 8
;         for (int d4 = 0; d4 < 32; ++d4) {
;             const f32x4 k4 = kp[d4];
; #pragma unroll
;             for (int t = 0; t < 8; ++t) { const f32x4 q4 = *(const LAS f32x4*)(qs + t * 128 + 4 * d4); s[t] += (k4[0] * q4[0] + k4[1] * q4[1]) + (k4[2] * q4[2] + k4[3] * q4[3]); }
;         }
; #pragma unroll
;         for (int t = 0; t < 8; ++t) {
;             const float m = wave_max(s[t]); const float p = __expf(s[t] - m); const float l = wave_sum(p);
;             pT[key * 8 + t] = p;
;             if (lane == 0) { ml[(wave * 8 + t) * 2] = m; ml[(wave * 8 + t) * 2 + 1] = l; }
;         }
	ds_read_b128 v[2:5], v54 offset:0
	ds_read_b128 v[6:9], v54 offset:64
	ds_read_b128 v[10:13], v54 offset:128
	ds_read_b128 v[14:17], v54 offset:192
	ds_read_b128 v[18:21], v54 offset:256
	ds_read_b128 v[22:25], v54 offset:320
	ds_read_b128 v[26:29], v54 offset:384
	ds_read_b128 v[30:33], v54 offset:448
	s_waitcnt lgkmcnt(0)
	v_mfma_f32_16x16x4_f32 v[36:39], v64, v2, 0
	v_mfma_f32_16x16x4_f32 v[40:43], v96, v2, 0
	v_mfma_f32_16x16x4_f32 v[36:39], v65, v3, v[36:39]
	v_mfma_f32_16x16x4_f32 v[40:43], v97, v3, v[40:43]
	v_mfma_f32_16x16x4_f32 v[36:39], v66, v4, v[36:39]
	v_mfma_f32_16x16x4_f32 v[40:43], v98, v4, v[40:43]
	v_mfma_f32_16x16x4_f32 v[36:39], v67, v5, v[36:39]
	v_mfma_f32_16x16x4_f32 v[40:43], v99, v5, v[40:43]
	v_mfma_f32_16x16x4_f32 v[36:39], v68, v6, v[36:39]
	v_mfma_f32_16x16x4_f32 v[40:43], v100, v6, v[40:43]
	v_mfma_f32_16x16x4_f32 v[36:39], v69, v7, v[36:39]
	v_mfma_f32_16x16x4_f32 v[40:43], v101, v7, v[40:43]
	v_mfma_f32_16x16x4_f32 v[36:39], v70, v8, v[36:39]
	v_mfma_f32_16x16x4_f32 v[40:43], v102, v8, v[40:43]
	v_mfma_f32_16x16x4_f32 v[36:39], v71, v9, v[36:39]
	v_mfma_f32_16x16x4_f32 v[40:43], v103, v9, v[40:43]
	v_mfma_f32_16x16x4_f32 v[36:39], v72, v10, v[36:39]
	v_mfma_f32_16x16x4_f32 v[40:43], v104, v10, v[40:43]
	v_mfma_f32_16x16x4_f32 v[36:39], v73, v11, v[36:39]
	v_mfma_f32_16x16x4_f32 v[40:43], v105, v11, v[40:43]
	v_mfma_f32_16x16x4_f32 v[36:39], v74, v12, v[36:39]
	v_mfma_f32_16x16x4_f32 v[40:43], v106, v12, v[40:43]
	v_mfma_f32_16x16x4_f32 v[36:39], v75, v13, v[36:39]
	v_mfma_f32_16x16x4_f32 v[40:43], v107, v13, v[40:43]
	v_mfma_f32_16x16x4_f32 v[36:39], v76, v14, v[36:39]
	v_mfma_f32_16x16x4_f32 v[40:43], v108, v14, v[40:43]
	v_mfma_f32_16x16x4_f32 v[36:39], v77, v15, v[36:39]
	v_mfma_f32_16x16x4_f32 v[40:43], v109, v15, v[40:43]
	v_mfma_f32_16x16x4_f32 v[36:39], v78, v16, v[36:39]
	v_mfma_f32_16x16x4_f32 v[40:43], v110, v16, v[40:43]
	v_mfma_f32_16x16x4_f32 v[36:39], v79, v17, v[36:39]
	v_mfma_f32_16x16x4_f32 v[40:43], v111, v17, v[40:43]
	v_mfma_f32_16x16x4_f32 v[36:39], v80, v18, v[36:39]
	v_mfma_f32_16x16x4_f32 v[40:43], v112, v18, v[40:43]
	v_mfma_f32_16x16x4_f32 v[36:39], v81, v19, v[36:39]
	v_mfma_f32_16x16x4_f32 v[40:43], v113, v19, v[40:43]
	v_mfma_f32_16x16x4_f32 v[36:39], v82, v20, v[36:39]
	v_mfma_f32_16x16x4_f32 v[40:43], v114, v20, v[40:43]
	v_mfma_f32_16x16x4_f32 v[36:39], v83, v21, v[36:39]
	v_mfma_f32_16x16x4_f32 v[40:43], v115, v21, v[40:43]
	v_mfma_f32_16x16x4_f32 v[36:39], v84, v22, v[36:39]
	v_mfma_f32_16x16x4_f32 v[40:43], v116, v22, v[40:43]
	v_mfma_f32_16x16x4_f32 v[36:39], v85, v23, v[36:39]
	v_mfma_f32_16x16x4_f32 v[40:43], v117, v23, v[40:43]
	v_mfma_f32_16x16x4_f32 v[36:39], v86, v24, v[36:39]
	v_mfma_f32_16x16x4_f32 v[40:43], v118, v24, v[40:43]
	v_mfma_f32_16x16x4_f32 v[36:39], v87, v25, v[36:39]
	v_mfma_f32_16x16x4_f32 v[40:43], v119, v25, v[40:43]
	v_mfma_f32_16x16x4_f32 v[36:39], v88, v26, v[36:39]
	v_mfma_f32_16x16x4_f32 v[40:43], v120, v26, v[40:43]
	v_mfma_f32_16x16x4_f32 v[36:39], v89, v27, v[36:39]
	v_mfma_f32_16x16x4_f32 v[40:43], v121, v27, v[40:43]
	v_mfma_f32_16x16x4_f32 v[36:39], v90, v28, v[36:39]
	v_mfma_f32_16x16x4_f32 v[40:43], v122, v28, v[40:43]
	v_mfma_f32_16x16x4_f32 v[36:39], v91, v29, v[36:39]
	v_mfma_f32_16x16x4_f32 v[40:43], v123, v29, v[40:43]
	v_mfma_f32_16x16x4_f32 v[36:39], v92, v30, v[36:39]
	v_mfma_f32_16x16x4_f32 v[40:43], v124, v30, v[40:43]
	v_mfma_f32_16x16x4_f32 v[36:39], v93, v31, v[36:39]
	v_mfma_f32_16x16x4_f32 v[40:43], v125, v31, v[40:43]
	v_mfma_f32_16x16x4_f32 v[36:39], v94, v32, v[36:39]
	v_mfma_f32_16x16x4_f32 v[40:43], v126, v32, v[40:43]
	v_mfma_f32_16x16x4_f32 v[36:39], v95, v33, v[36:39]
	v_mfma_f32_16x16x4_f32 v[40:43], v127, v33, v[40:43]
	s_nop 7
	s_nop 3
	v_max3_f32 v44, v36, v37, v38
	v_max3_f32 v44, v44, v39, v40
	v_max3_f32 v44, v44, v41, v42
	v_max_f32_e32 v44, v44, v43
	ds_bpermute_b32 v46, v56, v44
	s_waitcnt lgkmcnt(0)
	v_max_f32_e32 v46, v46, v46
	v_max_f32_e32 v44, v44, v46
	ds_bpermute_b32 v46, v57, v44
	s_waitcnt lgkmcnt(0)
	v_max_f32_e32 v46, v46, v46
	v_max_f32_e32 v44, v44, v46
	v_mov_b32_e32 v45, 0
	v_sub_f32_e32 v36, v36, v44
	v_mul_f32_e32 v36, 0x3fb8aa3b, v36
	v_exp_f32_e32 v36, v36
	v_sub_f32_e32 v37, v37, v44
	v_mul_f32_e32 v37, 0x3fb8aa3b, v37
	v_exp_f32_e32 v37, v37
	v_add_f32_e32 v45, v36, v45
	v_sub_f32_e32 v38, v38, v44
	v_mul_f32_e32 v38, 0x3fb8aa3b, v38
	v_exp_f32_e32 v38, v38
	v_add_f32_e32 v45, v37, v45
	v_sub_f32_e32 v39, v39, v44
	v_mul_f32_e32 v39, 0x3fb8aa3b, v39
	v_exp_f32_e32 v39, v39
	v_add_f32_e32 v45, v38, v45
	v_sub_f32_e32 v40, v40, v44
	v_mul_f32_e32 v40, 0x3fb8aa3b, v40
	v_exp_f32_e32 v40, v40
	v_add_f32_e32 v45, v39, v45
	v_sub_f32_e32 v41, v41, v44
	v_mul_f32_e32 v41, 0x3fb8aa3b, v41
	v_exp_f32_e32 v41, v41
	v_add_f32_e32 v45, v40, v45
	v_sub_f32_e32 v42, v42, v44
	v_mul_f32_e32 v42, 0x3fb8aa3b, v42
	v_exp_f32_e32 v42, v42
	v_add_f32_e32 v45, v41, v45
	v_sub_f32_e32 v43, v43, v44
	v_mul_f32_e32 v43, 0x3fb8aa3b, v43
	v_exp_f32_e32 v43, v43
	v_add_f32_e32 v45, v42, v45
	s_nop 0
	v_add_f32_e32 v45, v43, v45
	ds_bpermute_b32 v46, v56, v45
	s_waitcnt lgkmcnt(0)
	v_add_f32_e32 v45, v45, v46
	ds_bpermute_b32 v46, v57, v45
	s_waitcnt lgkmcnt(0)
	v_add_f32_e32 v45, v45, v46
	v_cmp_gt_u32_e32 vcc, 8, v215
	s_lshl_b32 s5, s29, 6
	v_lshl_add_u32 v46, v215, 3, s5
	v_add_u32_e32 v46, 0x1200, v46
	s_and_saveexec_b64 s[6:7], vcc
	ds_write_b64 v46, v[44:45]
	s_or_b64 exec, exec, s[6:7]
	s_waitcnt vmcnt(0)
; #define LAS __attribute__((address_space(3)))
; __device__ __forceinline__ void xattn_sample_block(LAS unsigned char* lds, const bf16_t* xq, const bf16_t* xq1, const float* mk, const float* mv, bf16_t* xo, int it, int tid) {
;     ...
;         f32x2 o[8];
; #pragma unroll
;         for (int t = 0; t < 8; ++t) o[t] = (f32x2){0.f, 0.f};
; #pragma unroll 16
;         for (int kk = 0; kk < 64; ++kk) {
;             const int k2 = 64 * wave + kk;
;             const f32x2 v = *(const f32x2*)(mv + (((size_t)b * 256 + k2) * 4 + h) * 128 + 2 * lane);
;             const f32x4 pa = *(const LAS f32x4*)(pT + k2 * 8), pb = *(const LAS f32x4*)(pT + k2 * 8 + 4);
;             o[0] += pa[0] * v; o[1] += pa[1] * v; o[2] += pa[2] * v; o[3] += pa[3] * v; o[4] += pb[0] * v; o[5] += pb[1] * v; o[6] += pb[2] * v; o[7] += pb[3] * v;
;         }
; #pragma unroll
;         for (int t = 0; t < 8; ++t) *(LAS f32x2*)(po + (wave * 8 + t) * 128 + 2 * lane) = o[t];
	v_mfma_f32_16x16x4_f32 v[2:5], v36, v146, 0
	v_mfma_f32_16x16x4_f32 v[6:9], v36, v147, 0
	v_mfma_f32_16x16x4_f32 v[10:13], v36, v148, 0
	v_mfma_f32_16x16x4_f32 v[14:17], v36, v149, 0
	v_mfma_f32_16x16x4_f32 v[18:21], v36, v150, 0
	v_mfma_f32_16x16x4_f32 v[22:25], v36, v151, 0
	v_mfma_f32_16x16x4_f32 v[26:29], v36, v152, 0
	v_mfma_f32_16x16x4_f32 v[30:33], v36, v153, 0
	v_mfma_f32_16x16x4_f32 v[2:5], v37, v154, v[2:5]
	v_mfma_f32_16x16x4_f32 v[6:9], v37, v155, v[6:9]
	v_mfma_f32_16x16x4_f32 v[10:13], v37, v156, v[10:13]
	v_mfma_f32_16x16x4_f32 v[14:17], v37, v157, v[14:17]
	v_mfma_f32_16x16x4_f32 v[18:21], v37, v158, v[18:21]
	v_mfma_f32_16x16x4_f32 v[22:25], v37, v159, v[22:25]
	v_mfma_f32_16x16x4_f32 v[26:29], v37, v160, v[26:29]
	v_mfma_f32_16x16x4_f32 v[30:33], v37, v161, v[30:33]
	v_mfma_f32_16x16x4_f32 v[2:5], v38, v162, v[2:5]
	v_mfma_f32_16x16x4_f32 v[6:9], v38, v163, v[6:9]
	v_mfma_f32_16x16x4_f32 v[10:13], v38, v164, v[10:13]
	v_mfma_f32_16x16x4_f32 v[14:17], v38, v165, v[14:17]
	v_mfma_f32_16x16x4_f32 v[18:21], v38, v166, v[18:21]
	v_mfma_f32_16x16x4_f32 v[22:25], v38, v167, v[22:25]
	v_mfma_f32_16x16x4_f32 v[26:29], v38, v168, v[26:29]
	v_mfma_f32_16x16x4_f32 v[30:33], v38, v169, v[30:33]
	v_mfma_f32_16x16x4_f32 v[2:5], v39, v170, v[2:5]
	v_mfma_f32_16x16x4_f32 v[6:9], v39, v171, v[6:9]
	v_mfma_f32_16x16x4_f32 v[10:13], v39, v172, v[10:13]
	v_mfma_f32_16x16x4_f32 v[14:17], v39, v173, v[14:17]
	v_mfma_f32_16x16x4_f32 v[18:21], v39, v174, v[18:21]
	v_mfma_f32_16x16x4_f32 v[22:25], v39, v175, v[22:25]
	v_mfma_f32_16x16x4_f32 v[26:29], v39, v176, v[26:29]
	v_mfma_f32_16x16x4_f32 v[30:33], v39, v177, v[30:33]
	v_mfma_f32_16x16x4_f32 v[2:5], v40, v178, v[2:5]
	v_mfma_f32_16x16x4_f32 v[6:9], v40, v179, v[6:9]
	v_mfma_f32_16x16x4_f32 v[10:13], v40, v180, v[10:13]
	v_mfma_f32_16x16x4_f32 v[14:17], v40, v181, v[14:17]
	v_mfma_f32_16x16x4_f32 v[18:21], v40, v182, v[18:21]
	v_mfma_f32_16x16x4_f32 v[22:25], v40, v183, v[22:25]
	v_mfma_f32_16x16x4_f32 v[26:29], v40, v184, v[26:29]
	v_mfma_f32_16x16x4_f32 v[30:33], v40, v185, v[30:33]
	v_mfma_f32_16x16x4_f32 v[2:5], v41, v186, v[2:5]
	v_mfma_f32_16x16x4_f32 v[6:9], v41, v187, v[6:9]
	v_mfma_f32_16x16x4_f32 v[10:13], v41, v188, v[10:13]
	v_mfma_f32_16x16x4_f32 v[14:17], v41, v189, v[14:17]
	v_mfma_f32_16x16x4_f32 v[18:21], v41, v190, v[18:21]
	v_mfma_f32_16x16x4_f32 v[22:25], v41, v191, v[22:25]
	v_mfma_f32_16x16x4_f32 v[26:29], v41, v192, v[26:29]
	v_mfma_f32_16x16x4_f32 v[30:33], v41, v193, v[30:33]
	v_mfma_f32_16x16x4_f32 v[2:5], v42, v194, v[2:5]
	v_mfma_f32_16x16x4_f32 v[6:9], v42, v195, v[6:9]
	v_mfma_f32_16x16x4_f32 v[10:13], v42, v196, v[10:13]
	v_mfma_f32_16x16x4_f32 v[14:17], v42, v197, v[14:17]
	v_mfma_f32_16x16x4_f32 v[18:21], v42, v198, v[18:21]
	v_mfma_f32_16x16x4_f32 v[22:25], v42, v199, v[22:25]
	v_mfma_f32_16x16x4_f32 v[26:29], v42, v200, v[26:29]
	v_mfma_f32_16x16x4_f32 v[30:33], v42, v201, v[30:33]
	v_mfma_f32_16x16x4_f32 v[2:5], v43, v202, v[2:5]
	v_mfma_f32_16x16x4_f32 v[6:9], v43, v203, v[6:9]
	v_mfma_f32_16x16x4_f32 v[10:13], v43, v204, v[10:13]
	v_mfma_f32_16x16x4_f32 v[14:17], v43, v205, v[14:17]
	v_mfma_f32_16x16x4_f32 v[18:21], v43, v206, v[18:21]
	v_mfma_f32_16x16x4_f32 v[22:25], v43, v207, v[22:25]
	v_mfma_f32_16x16x4_f32 v[26:29], v43, v208, v[26:29]
	v_mfma_f32_16x16x4_f32 v[30:33], v43, v209, v[30:33]
	s_nop 7
	s_nop 3
	s_lshl_b32 s5, s29, 13
	v_lshl_add_u32 v46, v215, 4, s5
	v_add_u32_e32 v46, 0x2000, v46
	ds_write_b128 v46, v[2:5] offset:0
	ds_write_b128 v46, v[6:9] offset:1024
	ds_write_b128 v46, v[10:13] offset:2048
	ds_write_b128 v46, v[14:17] offset:3072
	ds_write_b128 v46, v[18:21] offset:4096
	ds_write_b128 v46, v[22:25] offset:5120
	ds_write_b128 v46, v[26:29] offset:6144
	ds_write_b128 v46, v[30:33] offset:7168
	s_waitcnt lgkmcnt(0)
	s_barrier
; #define LAS __attribute__((address_space(3)))
; __device__ __forceinline__ unsigned pk2(float lo, float hi) { return pg8::cvt_pk_bf16(lo, hi); }
; __device__ __forceinline__ void xattn_sample_block(LAS unsigned char* lds, const bf16_t* xq, const bf16_t* xq1, const float* mk, const float* mv, bf16_t* xo, int it, int tid) {
;     ...
;     if (wave < 4) {
; #pragma unroll
;         for (int t2 = 0; t2 < 2; ++t2) {
;             const int t = wave * 2 + t2;
;             float m = ml[(0 * 8 + t) * 2];
; #pragma unroll
;             for (int w = 1; w < 4; ++w) m = fmaxf(m, ml[(w * 8 + t) * 2]);
;             float den = 0.f; f32x2 acc = {0.f, 0.f};
; #pragma unroll
;             for (int w = 0; w < 4; ++w) {
;                 const float sc = __expf(ml[(w * 8 + t) * 2] - m);
;                 den += sc * ml[(w * 8 + t) * 2 + 1];
;                 acc += sc * *(const LAS f32x2*)(po + (w * 8 + t) * 128 + 2 * lane);
;             }
;             const float inv = 1.0f / den;
;             *(unsigned*)(xo + (tok0 + t) * 512 + h * 128 + 2 * lane) = pk2(acc[0] * inv, acc[1] * inv);
;         }
	v_lshlrev_b32_e32 v46, 3, v58
	v_add_u32_e32 v46, 0x1200, v46
	ds_read_b64 v[2:3], v46 offset:0
	ds_read_b64 v[4:5], v46 offset:64
	ds_read_b64 v[6:7], v46 offset:128
	ds_read_b64 v[8:9], v46 offset:192
	ds_read_b64 v[10:11], v46 offset:256
	ds_read_b64 v[12:13], v46 offset:320
	ds_read_b64 v[14:15], v46 offset:384
	ds_read_b64 v[16:17], v46 offset:448
	v_lshlrev_b32_e32 v47, 1, v59
	v_lshrrev_b32_e32 v48, 6, v47
	v_and_b32_e32 v49, 3, v47
	v_lshl_add_u32 v48, v48, 2, v49
	v_lshlrev_b32_e32 v48, 10, v48
	v_bfe_u32 v49, v47, 2, 4
	v_lshrrev_b32_e32 v60, 2, v58
	v_lshl_add_u32 v49, v60, 4, v49
	v_lshl_add_u32 v48, v49, 4, v48
	v_and_b32_e32 v49, 3, v58
	v_lshl_add_u32 v48, v49, 2, v48
	v_add_u32_e32 v48, 0x2000, v48
	ds_read_b32 v18, v48 offset:0
	ds_read_b32 v19, v48 offset:1024
	ds_read_b32 v20, v48 offset:8192
	ds_read_b32 v21, v48 offset:9216
	ds_read_b32 v22, v48 offset:16384
	ds_read_b32 v23, v48 offset:17408
	ds_read_b32 v24, v48 offset:24576
	ds_read_b32 v25, v48 offset:25600
	ds_read_b32 v26, v48 offset:32768
	ds_read_b32 v27, v48 offset:33792
	ds_read_b32 v28, v48 offset:40960
	ds_read_b32 v29, v48 offset:41984
	ds_read_b32 v30, v48 offset:49152
	ds_read_b32 v31, v48 offset:50176
	ds_read_b32 v32, v48 offset:57344
	ds_read_b32 v33, v48 offset:58368
	s_waitcnt lgkmcnt(0)
	v_max3_f32 v36, v2, v4, v6
	v_max3_f32 v36, v36, v8, v10
	v_max3_f32 v36, v36, v12, v14
	v_max_f32_e32 v36, v36, v16
	v_mov_b32_e32 v37, 0
	v_mov_b32_e32 v38, 0
	v_mov_b32_e32 v39, 0
	v_sub_f32_e32 v40, v2, v36
	v_mul_f32_e32 v40, 0x3fb8aa3b, v40
	v_exp_f32_e32 v40, v40
	s_nop 0
	v_fmac_f32_e32 v37, v40, v3
	v_fmac_f32_e32 v38, v40, v18
	v_fmac_f32_e32 v39, v40, v19
	v_sub_f32_e32 v40, v4, v36
	v_mul_f32_e32 v40, 0x3fb8aa3b, v40
	v_exp_f32_e32 v40, v40
	s_nop 0
	v_fmac_f32_e32 v37, v40, v5
	v_fmac_f32_e32 v38, v40, v20
	v_fmac_f32_e32 v39, v40, v21
	v_sub_f32_e32 v40, v6, v36
	v_mul_f32_e32 v40, 0x3fb8aa3b, v40
	v_exp_f32_e32 v40, v40
	s_nop 0
	v_fmac_f32_e32 v37, v40, v7
	v_fmac_f32_e32 v38, v40, v22
	v_fmac_f32_e32 v39, v40, v23
	v_sub_f32_e32 v40, v8, v36
	v_mul_f32_e32 v40, 0x3fb8aa3b, v40
	v_exp_f32_e32 v40, v40
	s_nop 0
	v_fmac_f32_e32 v37, v40, v9
	v_fmac_f32_e32 v38, v40, v24
	v_fmac_f32_e32 v39, v40, v25
	v_sub_f32_e32 v40, v10, v36
	v_mul_f32_e32 v40, 0x3fb8aa3b, v40
	v_exp_f32_e32 v40, v40
	s_nop 0
	v_fmac_f32_e32 v37, v40, v11
	v_fmac_f32_e32 v38, v40, v26
	v_fmac_f32_e32 v39, v40, v27
	v_sub_f32_e32 v40, v12, v36
	v_mul_f32_e32 v40, 0x3fb8aa3b, v40
	v_exp_f32_e32 v40, v40
	s_nop 0
	v_fmac_f32_e32 v37, v40, v13
	v_fmac_f32_e32 v38, v40, v28
	v_fmac_f32_e32 v39, v40, v29
	v_sub_f32_e32 v40, v14, v36
	v_mul_f32_e32 v40, 0x3fb8aa3b, v40
	v_exp_f32_e32 v40, v40
	s_nop 0
	v_fmac_f32_e32 v37, v40, v15
	v_fmac_f32_e32 v38, v40, v30
	v_fmac_f32_e32 v39, v40, v31
	v_sub_f32_e32 v40, v16, v36
	v_mul_f32_e32 v40, 0x3fb8aa3b, v40
	v_exp_f32_e32 v40, v40
	s_nop 0
	v_fmac_f32_e32 v37, v40, v17
	v_fmac_f32_e32 v38, v40, v32
	v_fmac_f32_e32 v39, v40, v33
	v_div_scale_f32 v40, s[6:7], v37, v37, 1.0
	v_rcp_f32_e32 v41, v40
	s_nop 0
	v_fma_f32 v42, -v40, v41, 1.0
	v_fmac_f32_e32 v41, v42, v41
	v_div_scale_f32 v42, vcc, 1.0, v37, 1.0
	v_mul_f32_e32 v43, v42, v41
	v_fma_f32 v44, -v40, v43, v42
	v_fmac_f32_e32 v43, v44, v41
	v_fma_f32 v40, -v40, v43, v42
	v_div_fmas_f32 v40, v40, v41, v43
	v_div_fixup_f32 v40, v40, v37, 1.0
	v_mul_f32_e32 v38, v38, v40
	v_mul_f32_e32 v39, v39, v40
	v_cvt_pk_bf16_f32 v38, v38, v39
	s_lshl_b32 s5, s4, 3
	s_addk_i32 s5, 0x2000
	s_lshl_b32 s5, s5, 10
	s_lshl_b32 s6, s31, 8
	s_add_i32 s5, s5, s6
	s_add_u32 s24, s14, s5
	s_addc_u32 s25, s15, 0
	v_lshlrev_b32_e32 v60, 10, v58
	v_lshl_add_u32 v60, v59, 2, v60
	global_store_dword v60, v38, s[24:25]
	v_readlane_b32 s5, v254, 28
	s_nop 1
	s_add_i32 s28, s28, s5
	s_cmpk_lt_i32 s28, 0x80
	s_waitcnt lgkmcnt(0)
	s_barrier
	s_cbranch_scc1 .Lxs_item
	v_readlane_b32 s21, v254, 29
